# attention hot QK block: K fragment LDS reads issued one pair ahead of the MFMAs, accumulator shift splat with 64-bit moves (both layers)
# baseline (speedup 1.0000x reference)
.LBB0_883:
	v_mad_u32_u24 v203, v203, s82, v201
	ds_read_b128 v[204:207], v203
	ds_read_b128 v[208:211], v203 offset:32
	ds_read_b128 v[246:249], v203 offset:64
	ds_read_b128 v[250:253], v203 offset:96
	s_nop 5
	v_xor_b32_e32 v80, 0x80000000, v199
	v_xor_b32_e32 v64, 0x80000000, v200
	v_xor_b32_e32 v81, 0x80000000, v199
	v_xor_b32_e32 v65, 0x80000000, v200
	v_mov_b64 v[82:83], v[80:81]
	v_mov_b64 v[66:67], v[64:65]
	v_mov_b64 v[84:85], v[80:81]
	v_mov_b64 v[68:69], v[64:65]
	v_mov_b64 v[86:87], v[80:81]
	v_mov_b64 v[70:71], v[64:65]
	v_mov_b64 v[88:89], v[80:81]
	v_mov_b64 v[72:73], v[64:65]
	v_mov_b64 v[90:91], v[80:81]
	v_mov_b64 v[74:75], v[64:65]
	v_mov_b64 v[92:93], v[80:81]
	v_mov_b64 v[76:77], v[64:65]
	v_mov_b64 v[94:95], v[80:81]
	v_mov_b64 v[78:79], v[64:65]
	s_waitcnt lgkmcnt(2)
	v_mfma_f32_32x32x16_bf16 v[80:95], v[204:207], v[96:99], v[80:95]
	v_mfma_f32_32x32x16_bf16 v[64:79], v[204:207], v[136:139], v[64:79]
	v_mfma_f32_32x32x16_bf16 v[80:95], v[208:211], v[100:103], v[80:95]
	v_mfma_f32_32x32x16_bf16 v[64:79], v[208:211], v[120:123], v[64:79]
	ds_read_b128 v[204:207], v203 offset:128
	ds_read_b128 v[208:211], v203 offset:160
	s_waitcnt lgkmcnt(2)
	v_mfma_f32_32x32x16_bf16 v[80:95], v[246:249], v[104:107], v[80:95]
	v_mfma_f32_32x32x16_bf16 v[64:79], v[246:249], v[124:127], v[64:79]
	v_mfma_f32_32x32x16_bf16 v[80:95], v[250:253], v[108:111], v[80:95]
	v_mfma_f32_32x32x16_bf16 v[64:79], v[250:253], v[128:131], v[64:79]
	s_waitcnt lgkmcnt(0)
	v_mfma_f32_32x32x16_bf16 v[80:95], v[204:207], v[112:115], v[80:95]
	v_mfma_f32_32x32x16_bf16 v[64:79], v[204:207], v[132:135], v[64:79]
	v_mfma_f32_32x32x16_bf16 v[80:95], v[208:211], v[116:119], v[80:95]
	v_mfma_f32_32x32x16_bf16 v[64:79], v[208:211], v[140:143], v[64:79]
	s_branch .LBB0_885

.LBB0_2117:
	v_mad_u32_u24 v203, v203, s81, v201
	ds_read_b128 v[204:207], v203
	ds_read_b128 v[208:211], v203 offset:32
	ds_read_b128 v[246:249], v203 offset:64
	ds_read_b128 v[250:253], v203 offset:96
	s_nop 5
	v_xor_b32_e32 v80, 0x80000000, v199
	v_xor_b32_e32 v64, 0x80000000, v200
	v_xor_b32_e32 v81, 0x80000000, v199
	v_xor_b32_e32 v65, 0x80000000, v200
	v_mov_b64 v[82:83], v[80:81]
	v_mov_b64 v[66:67], v[64:65]
	v_mov_b64 v[84:85], v[80:81]
	v_mov_b64 v[68:69], v[64:65]
	v_mov_b64 v[86:87], v[80:81]
	v_mov_b64 v[70:71], v[64:65]
	v_mov_b64 v[88:89], v[80:81]
	v_mov_b64 v[72:73], v[64:65]
	v_mov_b64 v[90:91], v[80:81]
	v_mov_b64 v[74:75], v[64:65]
	v_mov_b64 v[92:93], v[80:81]
	v_mov_b64 v[76:77], v[64:65]
	v_mov_b64 v[94:95], v[80:81]
	v_mov_b64 v[78:79], v[64:65]
	s_waitcnt lgkmcnt(2)
	v_mfma_f32_32x32x16_bf16 v[80:95], v[204:207], v[96:99], v[80:95]
	v_mfma_f32_32x32x16_bf16 v[64:79], v[204:207], v[136:139], v[64:79]
	v_mfma_f32_32x32x16_bf16 v[80:95], v[208:211], v[100:103], v[80:95]
	v_mfma_f32_32x32x16_bf16 v[64:79], v[208:211], v[120:123], v[64:79]
	ds_read_b128 v[204:207], v203 offset:128
	ds_read_b128 v[208:211], v203 offset:160
	s_waitcnt lgkmcnt(2)
	v_mfma_f32_32x32x16_bf16 v[80:95], v[246:249], v[104:107], v[80:95]
	v_mfma_f32_32x32x16_bf16 v[64:79], v[246:249], v[124:127], v[64:79]
	v_mfma_f32_32x32x16_bf16 v[80:95], v[250:253], v[108:111], v[80:95]
	v_mfma_f32_32x32x16_bf16 v[64:79], v[250:253], v[128:131], v[64:79]
	s_waitcnt lgkmcnt(0)
	v_mfma_f32_32x32x16_bf16 v[80:95], v[204:207], v[112:115], v[80:95]
	v_mfma_f32_32x32x16_bf16 v[64:79], v[204:207], v[132:135], v[64:79]
	v_mfma_f32_32x32x16_bf16 v[80:95], v[208:211], v[116:119], v[80:95]
	v_mfma_f32_32x32x16_bf16 v[64:79], v[208:211], v[140:143], v[64:79]
	s_branch .LBB0_2119
